# ph2 tail as 256 half tiles plus unused-half LDS reads skipped in all half-tile loops
# speedup vs baseline: 1.0024x; 1.0024x over previous
.LBB0_786:
	s_add_i32 s82, s18, 2
	s_cmp_eq_u32 s71, s18
	s_cselect_b32 s18, s42, s45
	s_cselect_b32 s19, s1, s55
	s_cselect_b32 s36, s44, s63
	s_cselect_b32 s37, s43, s81
	s_add_u32 s26, s18, 0x80
	s_addc_u32 s27, s19, 0
	s_add_i32 s83, 0, 0x10000
	v_add_u32_e32 v0, s83, v214
	s_add_i32 s86, 0, 0x14000
	ds_read_b128 v[58:61], v0
	ds_read_b128 v[66:69], v0 offset:1024
	ds_read_b128 v[74:77], v0 offset:2048
	ds_read_b128 v[78:81], v0 offset:3072
	v_add_u32_e32 v0, s86, v214
	ds_read_b128 v[146:149], v0
	ds_read_b128 v[150:153], v0 offset:1024
	ds_read_b128 v[154:157], v0 offset:2048
	ds_read_b128 v[158:161], v0 offset:3072
	s_add_u32 s84, s45, 0x3ff80
	s_addc_u32 s85, s55, 0
	ds_read_b128 v[162:165], v215
	ds_read_b128 v[194:197], v215 offset:1024
	ds_read_b128 v[198:201], v215 offset:2048
	ds_read_b128 v[202:205], v215 offset:3072
	ds_read_b128 v[206:209], v215 offset:4096
	ds_read_b128 v[210:213], v215 offset:5120
	ds_read_b128 v[216:219], v215 offset:6144
	ds_read_b128 v[220:223], v215 offset:7168
	s_add_i32 m0, s3, 0xc000
	v_lshl_add_u64 v[224:225], s[84:85], 0, v[166:167]
	global_load_lds_dwordx4 v[224:225], off
	v_lshl_add_u64 v[224:225], s[84:85], 0, v[170:171]
	s_add_i32 m0, s3, 0xe000
	s_nop 0
	global_load_lds_dwordx4 v[224:225], off
	s_waitcnt vmcnt(8)
	s_waitcnt lgkmcnt(0)
	s_barrier
	s_setprio 1
	s_waitcnt lgkmcnt(0)
	v_mfma_f32_16x16x32_bf16 v[142:145], v[58:61], v[162:165], v[142:145]
	v_mfma_f32_16x16x32_bf16 v[138:141], v[74:77], v[162:165], v[138:141]
	v_mfma_f32_16x16x32_bf16 v[126:129], v[58:61], v[198:201], v[126:129]
	v_mfma_f32_16x16x32_bf16 v[122:125], v[74:77], v[198:201], v[122:125]
	v_mfma_f32_16x16x32_bf16 v[110:113], v[58:61], v[206:209], v[110:113]
	v_mfma_f32_16x16x32_bf16 v[106:109], v[74:77], v[206:209], v[106:109]
	v_mfma_f32_16x16x32_bf16 v[94:97], v[58:61], v[216:219], v[94:97]
	v_mfma_f32_16x16x32_bf16 v[90:93], v[74:77], v[216:219], v[90:93]
	v_mfma_f32_16x16x32_bf16 v[142:145], v[66:69], v[194:197], v[142:145]
	v_mfma_f32_16x16x32_bf16 v[138:141], v[78:81], v[194:197], v[138:141]
	v_mfma_f32_16x16x32_bf16 v[126:129], v[66:69], v[202:205], v[126:129]
	v_mfma_f32_16x16x32_bf16 v[122:125], v[78:81], v[202:205], v[122:125]
	v_mfma_f32_16x16x32_bf16 v[110:113], v[66:69], v[210:213], v[110:113]
	v_mfma_f32_16x16x32_bf16 v[106:109], v[78:81], v[210:213], v[106:109]
	v_mfma_f32_16x16x32_bf16 v[94:97], v[66:69], v[220:223], v[94:97]
	v_mfma_f32_16x16x32_bf16 v[90:93], v[78:81], v[220:223], v[90:93]
	v_mfma_f32_16x16x32_bf16 v[134:137], v[146:149], v[162:165], v[134:137]
	v_mfma_f32_16x16x32_bf16 v[130:133], v[154:157], v[162:165], v[130:133]
	v_mfma_f32_16x16x32_bf16 v[118:121], v[146:149], v[198:201], v[118:121]
	v_mfma_f32_16x16x32_bf16 v[114:117], v[154:157], v[198:201], v[114:117]
	v_mfma_f32_16x16x32_bf16 v[102:105], v[146:149], v[206:209], v[102:105]
	v_mfma_f32_16x16x32_bf16 v[98:101], v[154:157], v[206:209], v[98:101]
	v_mfma_f32_16x16x32_bf16 v[86:89], v[146:149], v[216:219], v[86:89]
	v_mfma_f32_16x16x32_bf16 v[82:85], v[154:157], v[216:219], v[82:85]
	v_mfma_f32_16x16x32_bf16 v[134:137], v[150:153], v[194:197], v[134:137]
	v_mfma_f32_16x16x32_bf16 v[130:133], v[158:161], v[194:197], v[130:133]
	v_mfma_f32_16x16x32_bf16 v[118:121], v[150:153], v[202:205], v[118:121]
	v_mfma_f32_16x16x32_bf16 v[114:117], v[158:161], v[202:205], v[114:117]
	v_mfma_f32_16x16x32_bf16 v[102:105], v[150:153], v[210:213], v[102:105]
	v_mfma_f32_16x16x32_bf16 v[98:101], v[158:161], v[210:213], v[98:101]
	v_mfma_f32_16x16x32_bf16 v[86:89], v[150:153], v[220:223], v[86:89]
	v_mfma_f32_16x16x32_bf16 v[82:85], v[158:161], v[220:223], v[82:85]
	s_setprio 0
	s_barrier
	s_mov_b64 s[84:85], s[36:37]
	s_add_i32 s83, s83, s25
	s_cmp_lg_u32 s100, 0
	s_cbranch_scc1 .Lh2_m0_r
	ds_read_b128 v[162:165], v215 offset:16384
	ds_read_b128 v[194:197], v215 offset:17408
	ds_read_b128 v[198:201], v215 offset:18432
	ds_read_b128 v[202:205], v215 offset:19456
	ds_read_b128 v[206:209], v215 offset:20480
	ds_read_b128 v[210:213], v215 offset:21504
	ds_read_b128 v[216:219], v215 offset:22528
	ds_read_b128 v[220:223], v215 offset:23552
.Lh2_m0_r:
	s_mov_b32 m0, s83
	v_lshl_add_u64 v[224:225], s[84:85], 0, v[168:169]
	global_load_lds_dwordx4 v[224:225], off
	s_add_i32 m0, s83, 0x2000
	v_lshl_add_u64 v[224:225], s[84:85], 0, v[172:173]
	s_add_u32 s84, s36, 0x40000
	s_addc_u32 s85, s37, 0
	s_add_i32 s83, s86, s25
	global_load_lds_dwordx4 v[224:225], off
	s_mov_b32 m0, s83
	v_lshl_add_u64 v[224:225], s[84:85], 0, v[168:169]
	global_load_lds_dwordx4 v[224:225], off
	v_lshl_add_u64 v[224:225], s[84:85], 0, v[172:173]
	s_add_i32 m0, s83, 0x2000
	s_mov_b64 s[84:85], s[18:19]
	global_load_lds_dwordx4 v[224:225], off
	s_mov_b32 m0, s3
	v_lshl_add_u64 v[224:225], s[84:85], 0, v[166:167]
	global_load_lds_dwordx4 v[224:225], off
	v_lshl_add_u64 v[224:225], s[84:85], 0, v[170:171]
	s_mov_b32 m0, s39
	s_nop 0
	global_load_lds_dwordx4 v[224:225], off
	s_waitcnt vmcnt(8)
	s_waitcnt lgkmcnt(0)
	s_barrier
	s_setprio 1
	s_waitcnt lgkmcnt(0)
	s_cmp_lg_u32 s100, 0
	s_cbranch_scc1 .Lh2_m0
	v_mfma_f32_16x16x32_bf16 v[70:73], v[58:61], v[162:165], v[70:73]
	v_mfma_f32_16x16x32_bf16 v[62:65], v[74:77], v[162:165], v[62:65]
	v_mfma_f32_16x16x32_bf16 v[46:49], v[58:61], v[198:201], v[46:49]
	v_mfma_f32_16x16x32_bf16 v[42:45], v[74:77], v[198:201], v[42:45]
	v_mfma_f32_16x16x32_bf16 v[30:33], v[58:61], v[206:209], v[30:33]
	v_mfma_f32_16x16x32_bf16 v[26:29], v[74:77], v[206:209], v[26:29]
	v_mfma_f32_16x16x32_bf16 v[14:17], v[58:61], v[216:219], v[14:17]
	v_mfma_f32_16x16x32_bf16 v[10:13], v[74:77], v[216:219], v[10:13]
	v_mfma_f32_16x16x32_bf16 v[70:73], v[66:69], v[194:197], v[70:73]
	v_mfma_f32_16x16x32_bf16 v[62:65], v[78:81], v[194:197], v[62:65]
	v_mfma_f32_16x16x32_bf16 v[46:49], v[66:69], v[202:205], v[46:49]
	v_mfma_f32_16x16x32_bf16 v[42:45], v[78:81], v[202:205], v[42:45]
	v_mfma_f32_16x16x32_bf16 v[30:33], v[66:69], v[210:213], v[30:33]
	v_mfma_f32_16x16x32_bf16 v[26:29], v[78:81], v[210:213], v[26:29]
	v_mfma_f32_16x16x32_bf16 v[14:17], v[66:69], v[220:223], v[14:17]
	v_mfma_f32_16x16x32_bf16 v[10:13], v[78:81], v[220:223], v[10:13]
	v_mfma_f32_16x16x32_bf16 v[54:57], v[146:149], v[162:165], v[54:57]
	v_mfma_f32_16x16x32_bf16 v[50:53], v[154:157], v[162:165], v[50:53]
	v_mfma_f32_16x16x32_bf16 v[38:41], v[146:149], v[198:201], v[38:41]
	v_mfma_f32_16x16x32_bf16 v[34:37], v[154:157], v[198:201], v[34:37]
	v_mfma_f32_16x16x32_bf16 v[22:25], v[146:149], v[206:209], v[22:25]
	v_mfma_f32_16x16x32_bf16 v[18:21], v[154:157], v[206:209], v[18:21]
	v_mfma_f32_16x16x32_bf16 v[6:9], v[146:149], v[216:219], v[6:9]
	v_mfma_f32_16x16x32_bf16 v[2:5], v[154:157], v[216:219], v[2:5]
	v_mfma_f32_16x16x32_bf16 v[54:57], v[150:153], v[194:197], v[54:57]
	v_mfma_f32_16x16x32_bf16 v[50:53], v[158:161], v[194:197], v[50:53]
	v_mfma_f32_16x16x32_bf16 v[38:41], v[150:153], v[202:205], v[38:41]
	v_mfma_f32_16x16x32_bf16 v[34:37], v[158:161], v[202:205], v[34:37]
	v_mfma_f32_16x16x32_bf16 v[22:25], v[150:153], v[210:213], v[22:25]
	v_mfma_f32_16x16x32_bf16 v[18:21], v[158:161], v[210:213], v[18:21]
	v_mfma_f32_16x16x32_bf16 v[6:9], v[150:153], v[220:223], v[6:9]
	v_mfma_f32_16x16x32_bf16 v[2:5], v[158:161], v[220:223], v[2:5]
.Lh2_m0:
	s_setprio 0
	s_barrier
	s_add_i32 s83, 0, 0x18000
	v_add_u32_e32 v0, s83, v214
	s_add_i32 s84, 0, 0x1c000
	ds_read_b128 v[58:61], v0
	ds_read_b128 v[66:69], v0 offset:1024
	ds_read_b128 v[74:77], v0 offset:2048
	ds_read_b128 v[78:81], v0 offset:3072
	v_add_u32_e32 v0, s84, v214
	ds_read_b128 v[146:149], v0
	ds_read_b128 v[150:153], v0 offset:1024
	ds_read_b128 v[154:157], v0 offset:2048
	ds_read_b128 v[158:161], v0 offset:3072
	s_add_u32 s18, s18, 0x40000
	s_addc_u32 s19, s19, 0
	s_mov_b32 m0, s67
	ds_read_b128 v[162:165], v215 offset:32768
	ds_read_b128 v[194:197], v215 offset:33792
	ds_read_b128 v[198:201], v215 offset:34816
	ds_read_b128 v[202:205], v215 offset:35840
	ds_read_b128 v[206:209], v215 offset:36864
	ds_read_b128 v[210:213], v215 offset:37888
	ds_read_b128 v[216:219], v215 offset:38912
	ds_read_b128 v[220:223], v215 offset:39936
	s_nop 0
	v_lshl_add_u64 v[224:225], s[18:19], 0, v[166:167]
	global_load_lds_dwordx4 v[224:225], off
	v_lshl_add_u64 v[224:225], s[18:19], 0, v[170:171]
	s_mov_b32 m0, s68
	s_nop 0
	global_load_lds_dwordx4 v[224:225], off
	s_waitcnt vmcnt(8)
	s_waitcnt lgkmcnt(0)
	s_barrier
	s_setprio 1
	s_waitcnt lgkmcnt(0)
	v_mfma_f32_16x16x32_bf16 v[142:145], v[58:61], v[162:165], v[142:145]
	v_mfma_f32_16x16x32_bf16 v[138:141], v[74:77], v[162:165], v[138:141]
	v_mfma_f32_16x16x32_bf16 v[126:129], v[58:61], v[198:201], v[126:129]
	v_mfma_f32_16x16x32_bf16 v[122:125], v[74:77], v[198:201], v[122:125]
	v_mfma_f32_16x16x32_bf16 v[110:113], v[58:61], v[206:209], v[110:113]
	v_mfma_f32_16x16x32_bf16 v[106:109], v[74:77], v[206:209], v[106:109]
	v_mfma_f32_16x16x32_bf16 v[94:97], v[58:61], v[216:219], v[94:97]
	v_mfma_f32_16x16x32_bf16 v[90:93], v[74:77], v[216:219], v[90:93]
	v_mfma_f32_16x16x32_bf16 v[142:145], v[66:69], v[194:197], v[142:145]
	v_mfma_f32_16x16x32_bf16 v[138:141], v[78:81], v[194:197], v[138:141]
	v_mfma_f32_16x16x32_bf16 v[126:129], v[66:69], v[202:205], v[126:129]
	v_mfma_f32_16x16x32_bf16 v[122:125], v[78:81], v[202:205], v[122:125]
	v_mfma_f32_16x16x32_bf16 v[110:113], v[66:69], v[210:213], v[110:113]
	v_mfma_f32_16x16x32_bf16 v[106:109], v[78:81], v[210:213], v[106:109]
	v_mfma_f32_16x16x32_bf16 v[94:97], v[66:69], v[220:223], v[94:97]
	v_mfma_f32_16x16x32_bf16 v[90:93], v[78:81], v[220:223], v[90:93]
	v_mfma_f32_16x16x32_bf16 v[134:137], v[146:149], v[162:165], v[134:137]
	v_mfma_f32_16x16x32_bf16 v[130:133], v[154:157], v[162:165], v[130:133]
	v_mfma_f32_16x16x32_bf16 v[118:121], v[146:149], v[198:201], v[118:121]
	v_mfma_f32_16x16x32_bf16 v[114:117], v[154:157], v[198:201], v[114:117]
	v_mfma_f32_16x16x32_bf16 v[102:105], v[146:149], v[206:209], v[102:105]
	v_mfma_f32_16x16x32_bf16 v[98:101], v[154:157], v[206:209], v[98:101]
	v_mfma_f32_16x16x32_bf16 v[86:89], v[146:149], v[216:219], v[86:89]
	v_mfma_f32_16x16x32_bf16 v[82:85], v[154:157], v[216:219], v[82:85]
	v_mfma_f32_16x16x32_bf16 v[134:137], v[150:153], v[194:197], v[134:137]
	v_mfma_f32_16x16x32_bf16 v[130:133], v[158:161], v[194:197], v[130:133]
	v_mfma_f32_16x16x32_bf16 v[118:121], v[150:153], v[202:205], v[118:121]
	v_mfma_f32_16x16x32_bf16 v[114:117], v[158:161], v[202:205], v[114:117]
	v_mfma_f32_16x16x32_bf16 v[102:105], v[150:153], v[210:213], v[102:105]
	v_mfma_f32_16x16x32_bf16 v[98:101], v[158:161], v[210:213], v[98:101]
	v_mfma_f32_16x16x32_bf16 v[86:89], v[150:153], v[220:223], v[86:89]
	v_mfma_f32_16x16x32_bf16 v[82:85], v[158:161], v[220:223], v[82:85]
	s_setprio 0
	s_barrier
	s_add_u32 s18, s36, 0x80
	s_addc_u32 s19, s37, 0
	s_add_i32 s83, s83, s25
	s_cmp_lg_u32 s100, 0
	s_cbranch_scc1 .Lh2_m1_r
	ds_read_b128 v[162:165], v215 offset:49152
	ds_read_b128 v[194:197], v215 offset:50176
	ds_read_b128 v[198:201], v215 offset:51200
	ds_read_b128 v[202:205], v215 offset:52224
	ds_read_b128 v[206:209], v215 offset:53248
	ds_read_b128 v[210:213], v215 offset:54272
	ds_read_b128 v[216:219], v215 offset:55296
	ds_read_b128 v[220:223], v215 offset:56320
.Lh2_m1_r:
	s_mov_b32 m0, s83
	v_lshl_add_u64 v[224:225], s[18:19], 0, v[168:169]
	global_load_lds_dwordx4 v[224:225], off
	s_add_i32 m0, s83, 0x2000
	v_lshl_add_u64 v[224:225], s[18:19], 0, v[172:173]
	s_add_u32 s18, s36, 0x40080
	s_addc_u32 s19, s37, 0
	s_add_i32 s36, s84, s25
	global_load_lds_dwordx4 v[224:225], off
	s_mov_b32 m0, s36
	v_lshl_add_u64 v[224:225], s[18:19], 0, v[168:169]
	global_load_lds_dwordx4 v[224:225], off
	v_lshl_add_u64 v[224:225], s[18:19], 0, v[172:173]
	s_add_i32 m0, s36, 0x2000
	s_nop 0
	global_load_lds_dwordx4 v[224:225], off
	s_mov_b32 m0, s72
	v_lshl_add_u64 v[224:225], s[26:27], 0, v[166:167]
	global_load_lds_dwordx4 v[224:225], off
	v_lshl_add_u64 v[224:225], s[26:27], 0, v[170:171]
	s_mov_b32 m0, s73
	s_nop 0
	global_load_lds_dwordx4 v[224:225], off
	s_waitcnt vmcnt(8)
	s_waitcnt lgkmcnt(0)
	s_barrier
	s_setprio 1
	s_waitcnt lgkmcnt(0)
	s_cmp_lg_u32 s100, 0
	s_cbranch_scc1 .Lh2_m1
	v_mfma_f32_16x16x32_bf16 v[70:73], v[58:61], v[162:165], v[70:73]
	v_mfma_f32_16x16x32_bf16 v[62:65], v[74:77], v[162:165], v[62:65]
	v_mfma_f32_16x16x32_bf16 v[46:49], v[58:61], v[198:201], v[46:49]
	v_mfma_f32_16x16x32_bf16 v[42:45], v[74:77], v[198:201], v[42:45]
	v_mfma_f32_16x16x32_bf16 v[30:33], v[58:61], v[206:209], v[30:33]
	v_mfma_f32_16x16x32_bf16 v[26:29], v[74:77], v[206:209], v[26:29]
	v_mfma_f32_16x16x32_bf16 v[14:17], v[58:61], v[216:219], v[14:17]
	v_mfma_f32_16x16x32_bf16 v[10:13], v[74:77], v[216:219], v[10:13]
	v_mfma_f32_16x16x32_bf16 v[70:73], v[66:69], v[194:197], v[70:73]
	v_mfma_f32_16x16x32_bf16 v[62:65], v[78:81], v[194:197], v[62:65]
	v_mfma_f32_16x16x32_bf16 v[46:49], v[66:69], v[202:205], v[46:49]
	v_mfma_f32_16x16x32_bf16 v[42:45], v[78:81], v[202:205], v[42:45]
	v_mfma_f32_16x16x32_bf16 v[30:33], v[66:69], v[210:213], v[30:33]
	v_mfma_f32_16x16x32_bf16 v[26:29], v[78:81], v[210:213], v[26:29]
	v_mfma_f32_16x16x32_bf16 v[14:17], v[66:69], v[220:223], v[14:17]
	v_mfma_f32_16x16x32_bf16 v[10:13], v[78:81], v[220:223], v[10:13]
	v_mfma_f32_16x16x32_bf16 v[54:57], v[146:149], v[162:165], v[54:57]
	v_mfma_f32_16x16x32_bf16 v[50:53], v[154:157], v[162:165], v[50:53]
	v_mfma_f32_16x16x32_bf16 v[38:41], v[146:149], v[198:201], v[38:41]
	v_mfma_f32_16x16x32_bf16 v[34:37], v[154:157], v[198:201], v[34:37]
	v_mfma_f32_16x16x32_bf16 v[22:25], v[146:149], v[206:209], v[22:25]
	v_mfma_f32_16x16x32_bf16 v[18:21], v[154:157], v[206:209], v[18:21]
	v_mfma_f32_16x16x32_bf16 v[6:9], v[146:149], v[216:219], v[6:9]
	v_mfma_f32_16x16x32_bf16 v[2:5], v[154:157], v[216:219], v[2:5]
	v_mfma_f32_16x16x32_bf16 v[54:57], v[150:153], v[194:197], v[54:57]
	v_mfma_f32_16x16x32_bf16 v[50:53], v[158:161], v[194:197], v[50:53]
	v_mfma_f32_16x16x32_bf16 v[38:41], v[150:153], v[202:205], v[38:41]
	v_mfma_f32_16x16x32_bf16 v[34:37], v[158:161], v[202:205], v[34:37]
	v_mfma_f32_16x16x32_bf16 v[22:25], v[150:153], v[210:213], v[22:25]
	v_mfma_f32_16x16x32_bf16 v[18:21], v[158:161], v[210:213], v[18:21]
	v_mfma_f32_16x16x32_bf16 v[6:9], v[150:153], v[220:223], v[6:9]
	v_mfma_f32_16x16x32_bf16 v[2:5], v[158:161], v[220:223], v[2:5]
